# attention: softmax exps merged with the P*V block on the common path and list-scheduled so exps issue in the MFMA shadow
# baseline (speedup 1.0000x reference)
; DI unsigned pk2(float lo, float hi) { f32x2 v = {lo, hi}; return __builtin_bit_cast(unsigned, __builtin_convertvector(v, bfx2)); }
; DI float ex2(float x) { return __builtin_amdgcn_exp2f(x); }
; DI f32x16 mfma32(bf16x8 a, bf16x8 b, f32x16 c) { return __builtin_amdgcn_mfma_f32_32x32x16_bf16(a, b, c, 0, 0, 0); }
; template <int MODE>
; DI void flash_pass(AState& st, const bf16x8* qf, u64 tmask, u64 wmask,
;                    const bf16_t* kbase, size_t kld, const bf16_t* kpe, const bf16_t* vtbase, const float* fbias,
;                    int tq, u64 mysel, bf16_t* smem) {
;     ...
;       for (int r = 0; r < 16; ++r) { e0[r] = ex2(s0[r]); e1[r] = ex2(s1[r]); }
;       if (__any(im > TBITS)) {
;         const float d = im > TBITS ? __int_as_float(im) : 0.f;
;         const float a = ex2(-d);
; #pragma unroll
;         for (int r = 0; r < 16; ++r) { e0[r] = ex2(s0[r] - d); e1[r] = ex2(s1[r] - d); st.o[0][r] *= a; st.o[1][r] *= a; }
;         st.l *= a; st.m += d;
; #pragma unroll
;         for (int r = 0; r < 16; ++r) st.mr[r] = -st.m;
;       }
;       float sum = 0.f;
; #pragma unroll
;       for (int r = 0; r < 16; ++r) { s0[r] = e0[r]; s1[r] = e1[r]; sum += e0[r] + e1[r]; }
;       st.l += sum;
;       const bf16_t* vr = Vs + l31 * 72 + half * 8;
; #pragma unroll
;       for (int c = 0; c < 4; ++c) {
;         u32x4 pw;
;         if (c < 2) pw = (u32x4){pk2(s0[8 * c + 0], s0[8 * c + 1]), pk2(s0[8 * c + 2], s0[8 * c + 3]), pk2(s0[8 * c + 4], s0[8 * c + 5]), pk2(s0[8 * c + 6], s0[8 * c + 7])};
;         else pw = (u32x4){pk2(s1[8 * (c - 2) + 0], s1[8 * (c - 2) + 1]), pk2(s1[8 * (c - 2) + 2], s1[8 * (c - 2) + 3]), pk2(s1[8 * (c - 2) + 4], s1[8 * (c - 2) + 5]), pk2(s1[8 * (c - 2) + 6], s1[8 * (c - 2) + 7])};
;         const bf16x8 pf = __builtin_bit_cast(bf16x8, pw);
;         st.o[0] = mfma32(*(const bf16x8*)(vr + c * 16), pf, st.o[0]);
;         st.o[1] = mfma32(*(const bf16x8*)(vr + 32 * 72 + c * 16), pf, st.o[1]);
;       }
.LBB0_614:
	ds_read_b128 v[242:245], v0 offset:9216
	ds_read_b128 v[246:249], v0 offset:9248
	v_exp_f32_e32 v151, v80
	v_exp_f32_e32 v147, v64
	v_exp_f32_e32 v152, v81
	v_exp_f32_e32 v148, v65
	v_exp_f32_e32 v153, v82
	v_exp_f32_e32 v149, v66
	v_exp_f32_e32 v154, v83
	v_exp_f32_e32 v150, v67
	v_exp_f32_e32 v80, v84
	v_exp_f32_e32 v10, v68
	v_exp_f32_e32 v81, v85
	v_exp_f32_e32 v11, v69
	v_exp_f32_e32 v82, v86
	v_exp_f32_e32 v12, v70
	v_exp_f32_e32 v83, v87
	v_exp_f32_e32 v13, v71
	v_exp_f32_e32 v14, v88
	v_exp_f32_e32 v2, v72
	v_exp_f32_e32 v15, v89
	v_exp_f32_e32 v3, v73
	v_exp_f32_e32 v64, v90
	v_exp_f32_e32 v4, v74
	v_exp_f32_e32 v65, v91
	v_exp_f32_e32 v5, v75
	v_exp_f32_e32 v66, v92
	v_exp_f32_e32 v6, v76
	v_exp_f32_e32 v67, v93
	v_exp_f32_e32 v7, v77
	v_exp_f32_e32 v68, v94
	v_exp_f32_e32 v8, v78
	v_exp_f32_e32 v69, v95
	v_exp_f32_e32 v9, v79
	v_add_f32_e32 v70, v151, v147
	v_add_f32_e32 v70, 0, v70
	v_add_f32_e32 v71, v152, v148
	v_add_f32_e32 v70, v71, v70
	v_add_f32_e32 v71, v153, v149
	v_add_f32_e32 v70, v71, v70
	v_add_f32_e32 v71, v154, v150
	v_add_f32_e32 v72, v71, v70
	v_pk_add_f32 v[70:71], v[80:81], v[10:11]
	v_cvt_pk_bf16_f32 v73, v82, v83
	v_add_f32_e32 v70, v70, v72
	v_add_f32_e32 v72, v71, v70
	v_pk_add_f32 v[70:71], v[82:83], v[12:13]
	v_add_f32_e32 v70, v70, v72
	v_add_f32_e32 v72, v71, v70
	v_pk_add_f32 v[70:71], v[14:15], v[2:3]
	v_add_f32_e32 v70, v70, v72
	v_add_f32_e32 v72, v71, v70
	v_pk_add_f32 v[70:71], v[64:65], v[4:5]
	v_add_f32_e32 v70, v70, v72
	v_add_f32_e32 v72, v71, v70
	v_pk_add_f32 v[70:71], v[66:67], v[6:7]
	v_add_f32_e32 v70, v70, v72
	v_add_f32_e32 v72, v71, v70
	v_pk_add_f32 v[70:71], v[68:69], v[8:9]
	v_add_f32_e32 v70, v70, v72
	v_cvt_pk_bf16_f32 v72, v80, v81
	v_add_f32_e32 v70, v71, v70
	v_add_f32_e32 v178, v178, v70
	v_cvt_pk_bf16_f32 v70, v151, v152
	v_cvt_pk_bf16_f32 v71, v153, v154
	s_waitcnt lgkmcnt(1)
	s_nop 0
	v_mfma_f32_32x32x16_bf16 v[32:47], v[242:245], v[70:73], v[32:47]
	v_cvt_pk_bf16_f32 v2, v2, v3
	v_cvt_pk_bf16_f32 v3, v4, v5
	v_cvt_pk_bf16_f32 v4, v6, v7
	v_cvt_pk_bf16_f32 v5, v8, v9
	ds_read_b128 v[6:9], v0 offset:9312
	ds_read_b128 v[250:253], v0 offset:13824
	s_waitcnt lgkmcnt(0)
	v_mfma_f32_32x32x16_bf16 v[16:31], v[250:253], v[70:73], v[16:31]
	v_cvt_pk_bf16_f32 v71, v64, v65
	v_cvt_pk_bf16_f32 v72, v66, v67
	ds_read_b128 v[64:67], v0 offset:13856
	v_cvt_pk_bf16_f32 v70, v14, v15
	v_cvt_pk_bf16_f32 v73, v68, v69
	s_waitcnt lgkmcnt(0)
	s_nop 0
	v_mfma_f32_32x32x16_bf16 v[16:31], v[64:67], v[70:73], v[16:31]
	v_mfma_f32_32x32x16_bf16 v[32:47], v[246:249], v[70:73], v[32:47]
	v_cvt_pk_bf16_f32 v66, v10, v11
	v_cvt_pk_bf16_f32 v67, v12, v13
	ds_read_b128 v[10:13], v0 offset:9280
	v_cvt_pk_bf16_f32 v64, v147, v148
	v_cvt_pk_bf16_f32 v65, v149, v150
	s_waitcnt lgkmcnt(0)
	s_nop 0
	v_mfma_f32_32x32x16_bf16 v[32:47], v[10:13], v[64:67], v[32:47]
	ds_read_b128 v[10:13], v0 offset:13888
	v_mfma_f32_32x32x16_bf16 v[32:47], v[6:9], v[2:5], v[32:47]
	ds_read_b128 v[6:9], v0 offset:13920
	s_waitcnt lgkmcnt(1)
	v_mfma_f32_32x32x16_bf16 v[16:31], v[10:13], v[64:67], v[16:31]
	s_waitcnt lgkmcnt(0)
	v_mfma_f32_32x32x16_bf16 v[16:31], v[6:9], v[2:5], v[16:31]
	s_nop 0
	s_nop 0
	s_branch .LBB0_616

; DI unsigned pk2(float lo, float hi) { f32x2 v = {lo, hi}; return __builtin_bit_cast(unsigned, __builtin_convertvector(v, bfx2)); }
; DI float ex2(float x) { return __builtin_amdgcn_exp2f(x); }
; DI f32x16 mfma32(bf16x8 a, bf16x8 b, f32x16 c) { return __builtin_amdgcn_mfma_f32_32x32x16_bf16(a, b, c, 0, 0, 0); }
; template <int MODE>
; DI void flash_pass(AState& st, const bf16x8* qf, u64 tmask, u64 wmask,
;                    const bf16_t* kbase, size_t kld, const bf16_t* kpe, const bf16_t* vtbase, const float* fbias,
;                    int tq, u64 mysel, bf16_t* smem) {
;     ...
;       for (int r = 0; r < 16; ++r) { e0[r] = ex2(s0[r]); e1[r] = ex2(s1[r]); }
;       if (__any(im > TBITS)) {
;         const float d = im > TBITS ? __int_as_float(im) : 0.f;
;         const float a = ex2(-d);
; #pragma unroll
;         for (int r = 0; r < 16; ++r) { e0[r] = ex2(s0[r] - d); e1[r] = ex2(s1[r] - d); st.o[0][r] *= a; st.o[1][r] *= a; }
;         st.l *= a; st.m += d;
; #pragma unroll
;         for (int r = 0; r < 16; ++r) st.mr[r] = -st.m;
;       }
;       float sum = 0.f;
; #pragma unroll
;       for (int r = 0; r < 16; ++r) { s0[r] = e0[r]; s1[r] = e1[r]; sum += e0[r] + e1[r]; }
;       st.l += sum;
;       const bf16_t* vr = Vs + l31 * 72 + half * 8;
; #pragma unroll
;       for (int c = 0; c < 4; ++c) {
;         u32x4 pw;
;         if (c < 2) pw = (u32x4){pk2(s0[8 * c + 0], s0[8 * c + 1]), pk2(s0[8 * c + 2], s0[8 * c + 3]), pk2(s0[8 * c + 4], s0[8 * c + 5]), pk2(s0[8 * c + 6], s0[8 * c + 7])};
;         else pw = (u32x4){pk2(s1[8 * (c - 2) + 0], s1[8 * (c - 2) + 1]), pk2(s1[8 * (c - 2) + 2], s1[8 * (c - 2) + 3]), pk2(s1[8 * (c - 2) + 4], s1[8 * (c - 2) + 5]), pk2(s1[8 * (c - 2) + 6], s1[8 * (c - 2) + 7])};
;         const bf16x8 pf = __builtin_bit_cast(bf16x8, pw);
;         st.o[0] = mfma32(*(const bf16x8*)(vr + c * 16), pf, st.o[0]);
;         st.o[1] = mfma32(*(const bf16x8*)(vr + 32 * 72 + c * 16), pf, st.o[1]);
;       }
.LBB0_643:
	ds_read_b128 v[242:245], v0 offset:9216
	ds_read_b128 v[246:249], v0 offset:9248
	ds_read_b128 v[250:253], v0 offset:13856
	v_exp_f32_e32 v194, v112
	v_exp_f32_e32 v192, v113
	v_exp_f32_e32 v191, v114
	v_exp_f32_e32 v114, v98
	v_exp_f32_e32 v193, v115
	v_exp_f32_e32 v115, v99
	v_exp_f32_e32 v112, v116
	v_exp_f32_e32 v113, v117
	v_exp_f32_e32 v2, v118
	v_exp_f32_e32 v6, v102
	v_exp_f32_e32 v3, v119
	v_exp_f32_e32 v7, v103
	v_exp_f32_e32 v98, v108
	v_exp_f32_e32 v99, v109
	v_exp_f32_e32 v102, v110
	v_exp_f32_e32 v103, v111
	v_cvt_pk_bf16_f32 v108, v194, v192
	v_cvt_pk_bf16_f32 v109, v191, v193
	v_cvt_pk_bf16_f32 v110, v112, v113
	v_cvt_pk_bf16_f32 v111, v2, v3
	s_waitcnt lgkmcnt(2)
	s_nop 0
	v_mfma_f32_32x32x16_bf16 v[64:79], v[242:245], v[108:111], v[64:79]
	v_exp_f32_e32 v4, v104
	v_exp_f32_e32 v5, v105
	v_exp_f32_e32 v12, v106
	v_exp_f32_e32 v13, v107
	ds_read_b128 v[104:107], v0 offset:13824
	s_waitcnt lgkmcnt(0)
	v_mfma_f32_32x32x16_bf16 v[48:63], v[104:107], v[108:111], v[48:63]
	v_exp_f32_e32 v189, v96
	v_exp_f32_e32 v190, v97
	v_exp_f32_e32 v8, v100
	v_exp_f32_e32 v9, v101
	v_exp_f32_e32 v10, v120
	v_exp_f32_e32 v11, v121
	v_exp_f32_e32 v14, v122
	v_exp_f32_e32 v15, v123
	v_exp_f32_e32 v96, v124
	v_exp_f32_e32 v97, v125
	v_exp_f32_e32 v100, v126
	v_exp_f32_e32 v101, v127
	v_add_f32_e32 v124, v194, v189
	v_add_f32_e32 v104, 0, v124
	v_add_f32_e32 v105, v192, v190
	v_add_f32_e32 v108, v105, v104
	v_cvt_pk_bf16_f32 v104, v10, v11
	v_cvt_pk_bf16_f32 v105, v14, v15
	v_cvt_pk_bf16_f32 v106, v96, v97
	v_cvt_pk_bf16_f32 v107, v100, v101
	s_nop 1
	v_mfma_f32_32x32x16_bf16 v[64:79], v[246:249], v[104:107], v[64:79]
	v_mfma_f32_32x32x16_bf16 v[48:63], v[250:253], v[104:107], v[48:63]
	v_pk_add_f32 v[112:113], v[112:113], v[8:9]
	v_add_f32_e32 v109, v191, v114
	v_add_f32_e32 v108, v109, v108
	v_add_f32_e32 v109, v193, v115
	v_add_f32_e32 v108, v109, v108
	v_add_f32_e32 v112, v112, v108
	ds_read_b128 v[108:111], v0 offset:9280
	v_cvt_pk_bf16_f32 v105, v114, v115
	v_cvt_pk_bf16_f32 v107, v6, v7
	v_cvt_pk_bf16_f32 v104, v189, v190
	v_cvt_pk_bf16_f32 v106, v8, v9
	s_waitcnt lgkmcnt(0)
	s_nop 0
	v_mfma_f32_32x32x16_bf16 v[64:79], v[108:111], v[104:107], v[64:79]
	v_add_f32_e32 v120, v113, v112
	ds_read_b128 v[112:115], v0 offset:13888
	ds_read_b128 v[116:119], v0 offset:9312
	s_waitcnt lgkmcnt(1)
	v_mfma_f32_32x32x16_bf16 v[48:63], v[112:115], v[104:107], v[48:63]
	v_add_f32_e64 v2, v2, v6
	v_add_f32_e64 v3, v3, v7
	v_add_f32_e32 v2, v2, v120
	v_add_f32_e32 v6, v3, v2
	v_pk_add_f32 v[2:3], v[10:11], v[4:5]
	v_add_f32_e32 v2, v2, v6
	ds_read_b128 v[6:9], v0 offset:13920
	v_add_f32_e32 v10, v3, v2
	v_add_f32_e64 v2, v14, v12
	v_add_f32_e64 v3, v15, v13
	v_add_f32_e32 v0, v2, v10
	v_add_f32_e32 v0, v3, v0
	v_cvt_pk_bf16_f32 v2, v4, v5
	v_cvt_pk_bf16_f32 v3, v12, v13
	v_cvt_pk_bf16_f32 v4, v98, v99
	v_cvt_pk_bf16_f32 v5, v102, v103
	s_waitcnt lgkmcnt(1)
	s_nop 0
	v_mfma_f32_32x32x16_bf16 v[64:79], v[116:119], v[2:5], v[64:79]
	s_waitcnt lgkmcnt(0)
	v_mfma_f32_32x32x16_bf16 v[48:63], v[6:9], v[2:5], v[48:63]
	v_add_f32_e64 v10, v96, v98
	v_add_f32_e64 v11, v97, v99
	v_add_f32_e32 v0, v10, v0
	v_add_f32_e32 v0, v11, v0
	v_pk_add_f32 v[10:11], v[100:101], v[102:103]
	v_add_f32_e32 v0, v10, v0
	v_add_f32_e32 v0, v11, v0
	v_add_f32_e32 v169, v169, v0
	s_branch .LBB0_645

; DI unsigned pk2(float lo, float hi) { f32x2 v = {lo, hi}; return __builtin_bit_cast(unsigned, __builtin_convertvector(v, bfx2)); }
; DI float ex2(float x) { return __builtin_amdgcn_exp2f(x); }
; DI f32x16 mfma32(bf16x8 a, bf16x8 b, f32x16 c) { return __builtin_amdgcn_mfma_f32_32x32x16_bf16(a, b, c, 0, 0, 0); }
; template <int MODE>
; DI void flash_pass(AState& st, const bf16x8* qf, u64 tmask, u64 wmask,
;                    const bf16_t* kbase, size_t kld, const bf16_t* kpe, const bf16_t* vtbase, const float* fbias,
;                    int tq, u64 mysel, bf16_t* smem) {
;     ...
;       for (int r = 0; r < 16; ++r) { e0[r] = ex2(s0[r]); e1[r] = ex2(s1[r]); }
;       if (__any(im > TBITS)) {
;         const float d = im > TBITS ? __int_as_float(im) : 0.f;
;         const float a = ex2(-d);
; #pragma unroll
;         for (int r = 0; r < 16; ++r) { e0[r] = ex2(s0[r] - d); e1[r] = ex2(s1[r] - d); st.o[0][r] *= a; st.o[1][r] *= a; }
;         st.l *= a; st.m += d;
; #pragma unroll
;         for (int r = 0; r < 16; ++r) st.mr[r] = -st.m;
;       }
;       float sum = 0.f;
; #pragma unroll
;       for (int r = 0; r < 16; ++r) { s0[r] = e0[r]; s1[r] = e1[r]; sum += e0[r] + e1[r]; }
;       st.l += sum;
;       const bf16_t* vr = Vs + l31 * 72 + half * 8;
; #pragma unroll
;       for (int c = 0; c < 4; ++c) {
;         u32x4 pw;
;         if (c < 2) pw = (u32x4){pk2(s0[8 * c + 0], s0[8 * c + 1]), pk2(s0[8 * c + 2], s0[8 * c + 3]), pk2(s0[8 * c + 4], s0[8 * c + 5]), pk2(s0[8 * c + 6], s0[8 * c + 7])};
;         else pw = (u32x4){pk2(s1[8 * (c - 2) + 0], s1[8 * (c - 2) + 1]), pk2(s1[8 * (c - 2) + 2], s1[8 * (c - 2) + 3]), pk2(s1[8 * (c - 2) + 4], s1[8 * (c - 2) + 5]), pk2(s1[8 * (c - 2) + 6], s1[8 * (c - 2) + 7])};
;         const bf16x8 pf = __builtin_bit_cast(bf16x8, pw);
;         st.o[0] = mfma32(*(const bf16x8*)(vr + c * 16), pf, st.o[0]);
;         st.o[1] = mfma32(*(const bf16x8*)(vr + 32 * 72 + c * 16), pf, st.o[1]);
;       }
.LBB0_691:
	v_exp_f32_e32 v98, v156
	v_exp_f32_e32 v94, v160
	v_exp_f32_e32 v99, v157
	v_exp_f32_e32 v95, v161
	v_exp_f32_e32 v100, v158
	v_exp_f32_e32 v96, v96
	v_exp_f32_e32 v101, v159
	v_exp_f32_e32 v97, v97
	v_exp_f32_e32 v90, v14
	v_exp_f32_e32 v14, v10
	v_exp_f32_e32 v91, v15
	v_exp_f32_e32 v15, v11
	v_exp_f32_e32 v92, v84
	v_exp_f32_e32 v80, v80
	v_exp_f32_e32 v93, v85
	v_exp_f32_e32 v81, v81
	v_exp_f32_e32 v84, v88
	v_exp_f32_e32 v10, v86
	v_exp_f32_e32 v85, v89
	v_exp_f32_e32 v11, v87
	v_exp_f32_e32 v82, v82
	v_exp_f32_e32 v12, v12
	v_exp_f32_e32 v83, v83
	v_exp_f32_e32 v13, v13
	v_exp_f32_e32 v8, v8
	v_exp_f32_e32 v6, v6
	v_exp_f32_e32 v9, v9
	v_exp_f32_e32 v7, v7
	v_exp_f32_e32 v86, v2
	v_exp_f32_e32 v2, v4
	v_exp_f32_e32 v87, v3
	v_exp_f32_e32 v3, v5
	v_add_f32_e32 v4, v98, v94
	v_add_f32_e32 v4, 0, v4
	v_add_f32_e32 v5, v99, v95
	v_add_f32_e32 v4, v5, v4
	v_add_f32_e32 v5, v100, v96
	v_add_f32_e32 v4, v5, v4
	v_add_f32_e32 v5, v101, v97
	v_add_f32_e32 v88, v5, v4
	v_pk_add_f32 v[4:5], v[90:91], v[14:15]
	v_cvt_pk_bf16_f32 v89, v100, v101
	v_add_f32_e32 v4, v4, v88
	v_add_f32_e32 v88, v5, v4
	v_pk_add_f32 v[4:5], v[92:93], v[80:81]
	v_cvt_pk_bf16_f32 v90, v90, v91
	v_add_f32_e32 v4, v4, v88
	v_add_f32_e32 v88, v5, v4
	v_pk_add_f32 v[4:5], v[84:85], v[10:11]
	v_cvt_pk_bf16_f32 v91, v92, v93
	v_add_f32_e32 v4, v4, v88
	v_add_f32_e32 v88, v5, v4
	v_pk_add_f32 v[4:5], v[82:83], v[12:13]
	v_add_f32_e32 v4, v4, v88
	v_add_f32_e32 v88, v5, v4
	v_pk_add_f32 v[4:5], v[8:9], v[6:7]
	v_add_f32_e32 v4, v4, v88
	v_add_f32_e32 v88, v5, v4
	v_pk_add_f32 v[4:5], v[86:87], v[2:3]
	v_add_f32_e32 v4, v4, v88
	v_cvt_pk_bf16_f32 v88, v98, v99
	ds_read_b128 v[98:101], v0 offset:9216
	ds_read_b128 v[102:105], v0 offset:9248
	s_waitcnt lgkmcnt(1)
	v_mfma_f32_32x32x16_bf16 v[32:47], v[98:101], v[88:91], v[32:47]
	ds_read_b128 v[98:101], v0 offset:13824
	ds_read_b128 v[242:245], v0 offset:13856
	ds_read_b128 v[246:249], v0 offset:9312
	ds_read_b128 v[250:253], v0 offset:9280
	s_waitcnt lgkmcnt(3)
	v_mfma_f32_32x32x16_bf16 v[16:31], v[98:101], v[88:91], v[16:31]
	v_cvt_pk_bf16_f32 v88, v84, v85
	v_cvt_pk_bf16_f32 v89, v82, v83
	v_cvt_pk_bf16_f32 v90, v8, v9
	v_cvt_pk_bf16_f32 v91, v86, v87
	s_nop 1
	v_mfma_f32_32x32x16_bf16 v[32:47], v[102:105], v[88:91], v[32:47]
	s_waitcnt lgkmcnt(2)
	v_mfma_f32_32x32x16_bf16 v[16:31], v[242:245], v[88:91], v[16:31]
	ds_read_b128 v[86:89], v0 offset:13888
	v_cvt_pk_bf16_f32 v82, v94, v95
	v_cvt_pk_bf16_f32 v83, v96, v97
	v_cvt_pk_bf16_f32 v84, v14, v15
	v_cvt_pk_bf16_f32 v85, v80, v81
	s_waitcnt lgkmcnt(1)
	s_nop 0
	v_mfma_f32_32x32x16_bf16 v[32:47], v[250:253], v[82:85], v[32:47]
	s_waitcnt lgkmcnt(0)
	v_mfma_f32_32x32x16_bf16 v[16:31], v[86:89], v[82:85], v[16:31]
	v_cvt_pk_bf16_f32 v6, v6, v7
	v_cvt_pk_bf16_f32 v7, v2, v3
	v_add_f32_e32 v4, v5, v4
	v_add_f32_e32 v176, v176, v4
	v_cvt_pk_bf16_f32 v4, v10, v11
	ds_read_b128 v[8:11], v0 offset:13920
	v_cvt_pk_bf16_f32 v5, v12, v13
	s_nop 1
	v_mfma_f32_32x32x16_bf16 v[32:47], v[246:249], v[4:7], v[32:47]
	s_waitcnt lgkmcnt(0)
	v_mfma_f32_32x32x16_bf16 v[16:31], v[8:11], v[4:7], v[16:31]
	s_nop 0
	s_nop 0
	s_nop 0
	s_branch .LBB0_693

; DI unsigned pk2(float lo, float hi) { f32x2 v = {lo, hi}; return __builtin_bit_cast(unsigned, __builtin_convertvector(v, bfx2)); }
; DI float ex2(float x) { return __builtin_amdgcn_exp2f(x); }
; DI f32x16 mfma32(bf16x8 a, bf16x8 b, f32x16 c) { return __builtin_amdgcn_mfma_f32_32x32x16_bf16(a, b, c, 0, 0, 0); }
; template <int MODE>
; DI void flash_pass(AState& st, const bf16x8* qf, u64 tmask, u64 wmask,
;                    const bf16_t* kbase, size_t kld, const bf16_t* kpe, const bf16_t* vtbase, const float* fbias,
;                    int tq, u64 mysel, bf16_t* smem) {
;     ...
;       for (int r = 0; r < 16; ++r) { e0[r] = ex2(s0[r]); e1[r] = ex2(s1[r]); }
;       if (__any(im > TBITS)) {
;         const float d = im > TBITS ? __int_as_float(im) : 0.f;
;         const float a = ex2(-d);
; #pragma unroll
;         for (int r = 0; r < 16; ++r) { e0[r] = ex2(s0[r] - d); e1[r] = ex2(s1[r] - d); st.o[0][r] *= a; st.o[1][r] *= a; }
;         st.l *= a; st.m += d;
; #pragma unroll
;         for (int r = 0; r < 16; ++r) st.mr[r] = -st.m;
;       }
;       float sum = 0.f;
; #pragma unroll
;       for (int r = 0; r < 16; ++r) { s0[r] = e0[r]; s1[r] = e1[r]; sum += e0[r] + e1[r]; }
;       st.l += sum;
;       const bf16_t* vr = Vs + l31 * 72 + half * 8;
; #pragma unroll
;       for (int c = 0; c < 4; ++c) {
;         u32x4 pw;
;         if (c < 2) pw = (u32x4){pk2(s0[8 * c + 0], s0[8 * c + 1]), pk2(s0[8 * c + 2], s0[8 * c + 3]), pk2(s0[8 * c + 4], s0[8 * c + 5]), pk2(s0[8 * c + 6], s0[8 * c + 7])};
;         else pw = (u32x4){pk2(s1[8 * (c - 2) + 0], s1[8 * (c - 2) + 1]), pk2(s1[8 * (c - 2) + 2], s1[8 * (c - 2) + 3]), pk2(s1[8 * (c - 2) + 4], s1[8 * (c - 2) + 5]), pk2(s1[8 * (c - 2) + 6], s1[8 * (c - 2) + 7])};
;         const bf16x8 pf = __builtin_bit_cast(bf16x8, pw);
;         st.o[0] = mfma32(*(const bf16x8*)(vr + c * 16), pf, st.o[0]);
;         st.o[1] = mfma32(*(const bf16x8*)(vr + 32 * 72 + c * 16), pf, st.o[1]);
;       }
.LBB0_759:
	v_exp_f32_e32 v183, v80
	v_exp_f32_e32 v178, v64
	v_exp_f32_e32 v181, v81
	v_exp_f32_e32 v180, v82
	v_exp_f32_e32 v82, v66
	v_exp_f32_e32 v182, v83
	v_exp_f32_e32 v83, v67
	v_exp_f32_e32 v80, v84
	v_exp_f32_e32 v81, v85
	v_exp_f32_e32 v2, v86
	v_exp_f32_e32 v6, v70
	v_exp_f32_e32 v3, v87
	v_exp_f32_e32 v7, v71
	v_exp_f32_e32 v4, v72
	v_exp_f32_e32 v64, v92
	v_exp_f32_e32 v66, v76
	v_exp_f32_e32 v67, v77
	v_exp_f32_e32 v70, v78
	v_exp_f32_e32 v71, v79
	v_lshlrev_b32_e32 v72, 1, v169
	v_add3_u32 v92, v177, v173, v72
	ds_read_b128 v[242:245], v92 offset:13312
	ds_read_b128 v[246:249], v92 offset:13344
	ds_read_b128 v[250:253], v92 offset:17952
	v_cvt_pk_bf16_f32 v76, v183, v181
	v_cvt_pk_bf16_f32 v77, v180, v182
	v_cvt_pk_bf16_f32 v78, v80, v81
	v_cvt_pk_bf16_f32 v79, v2, v3
	s_waitcnt lgkmcnt(2)
	s_nop 0
	v_mfma_f32_32x32x16_bf16 v[32:47], v[242:245], v[76:79], v[32:47]
	v_exp_f32_e32 v5, v73
	v_exp_f32_e32 v12, v74
	v_exp_f32_e32 v13, v75
	ds_read_b128 v[72:75], v92 offset:17920
	s_waitcnt lgkmcnt(0)
	v_mfma_f32_32x32x16_bf16 v[16:31], v[72:75], v[76:79], v[16:31]
	v_exp_f32_e32 v179, v65
	v_exp_f32_e32 v8, v68
	v_exp_f32_e32 v9, v69
	v_exp_f32_e32 v10, v88
	v_exp_f32_e32 v11, v89
	v_exp_f32_e32 v14, v90
	v_exp_f32_e32 v15, v91
	v_exp_f32_e32 v65, v93
	v_exp_f32_e32 v68, v94
	v_exp_f32_e32 v69, v95
	v_add_f32_e32 v93, v183, v178
	v_add_f32_e32 v72, 0, v93
	v_add_f32_e32 v73, v181, v179
	v_add_f32_e32 v76, v73, v72
	v_cvt_pk_bf16_f32 v72, v10, v11
	v_cvt_pk_bf16_f32 v73, v14, v15
	v_cvt_pk_bf16_f32 v74, v64, v65
	v_cvt_pk_bf16_f32 v75, v68, v69
	s_nop 1
	v_mfma_f32_32x32x16_bf16 v[32:47], v[246:249], v[72:75], v[32:47]
	v_mfma_f32_32x32x16_bf16 v[16:31], v[250:253], v[72:75], v[16:31]
	v_pk_add_f32 v[80:81], v[80:81], v[8:9]
	v_add_f32_e32 v77, v180, v82
	v_add_f32_e32 v76, v77, v76
	v_add_f32_e32 v77, v182, v83
	v_add_f32_e32 v76, v77, v76
	v_add_f32_e32 v80, v80, v76
	ds_read_b128 v[76:79], v92 offset:13376
	v_cvt_pk_bf16_f32 v73, v82, v83
	v_cvt_pk_bf16_f32 v75, v6, v7
	v_cvt_pk_bf16_f32 v72, v178, v179
	v_cvt_pk_bf16_f32 v74, v8, v9
	s_waitcnt lgkmcnt(0)
	s_nop 0
	v_mfma_f32_32x32x16_bf16 v[32:47], v[76:79], v[72:75], v[32:47]
	v_add_f32_e32 v88, v81, v80
	ds_read_b128 v[80:83], v92 offset:17984
	ds_read_b128 v[84:87], v92 offset:13408
	s_waitcnt lgkmcnt(1)
	v_mfma_f32_32x32x16_bf16 v[16:31], v[80:83], v[72:75], v[16:31]
	v_add_f32_e64 v2, v2, v6
	v_add_f32_e64 v3, v3, v7
	v_add_f32_e32 v2, v2, v88
	v_add_f32_e32 v6, v3, v2
	v_pk_add_f32 v[2:3], v[10:11], v[4:5]
	v_add_f32_e32 v2, v2, v6
	ds_read_b128 v[6:9], v92 offset:18016
	v_add_f32_e32 v10, v3, v2
	v_add_f32_e64 v2, v14, v12
	v_add_f32_e64 v3, v15, v13
	v_add_f32_e32 v2, v2, v10
	v_add_f32_e32 v14, v3, v2
	v_cvt_pk_bf16_f32 v2, v4, v5
	v_cvt_pk_bf16_f32 v3, v12, v13
	v_cvt_pk_bf16_f32 v4, v66, v67
	v_cvt_pk_bf16_f32 v5, v70, v71
	s_waitcnt lgkmcnt(1)
	s_nop 0
	v_mfma_f32_32x32x16_bf16 v[32:47], v[84:87], v[2:5], v[32:47]
	s_waitcnt lgkmcnt(0)
	v_mfma_f32_32x32x16_bf16 v[16:31], v[6:9], v[2:5], v[16:31]
	v_add_f32_e64 v10, v64, v66
	v_add_f32_e64 v11, v65, v67
	v_add_f32_e32 v10, v10, v14
	v_add_f32_e32 v12, v11, v10
	v_pk_add_f32 v[10:11], v[68:69], v[70:71]
	v_add_f32_e32 v10, v10, v12
	v_add_f32_e32 v10, v11, v10
	v_add_f32_e32 v171, v171, v10
	s_branch .LBB0_761

; DI unsigned pk2(float lo, float hi) { f32x2 v = {lo, hi}; return __builtin_bit_cast(unsigned, __builtin_convertvector(v, bfx2)); }
; DI float ex2(float x) { return __builtin_amdgcn_exp2f(x); }
; DI f32x16 mfma32(bf16x8 a, bf16x8 b, f32x16 c) { return __builtin_amdgcn_mfma_f32_32x32x16_bf16(a, b, c, 0, 0, 0); }
; template <int MODE>
; DI void flash_pass(AState& st, const bf16x8* qf, u64 tmask, u64 wmask,
;                    const bf16_t* kbase, size_t kld, const bf16_t* kpe, const bf16_t* vtbase, const float* fbias,
;                    int tq, u64 mysel, bf16_t* smem) {
;     ...
;       for (int r = 0; r < 16; ++r) { e0[r] = ex2(s0[r]); e1[r] = ex2(s1[r]); }
;       if (__any(im > TBITS)) {
;         const float d = im > TBITS ? __int_as_float(im) : 0.f;
;         const float a = ex2(-d);
; #pragma unroll
;         for (int r = 0; r < 16; ++r) { e0[r] = ex2(s0[r] - d); e1[r] = ex2(s1[r] - d); st.o[0][r] *= a; st.o[1][r] *= a; }
;         st.l *= a; st.m += d;
; #pragma unroll
;         for (int r = 0; r < 16; ++r) st.mr[r] = -st.m;
;       }
;       float sum = 0.f;
; #pragma unroll
;       for (int r = 0; r < 16; ++r) { s0[r] = e0[r]; s1[r] = e1[r]; sum += e0[r] + e1[r]; }
;       st.l += sum;
;       const bf16_t* vr = Vs + l31 * 72 + half * 8;
; #pragma unroll
;       for (int c = 0; c < 4; ++c) {
;         u32x4 pw;
;         if (c < 2) pw = (u32x4){pk2(s0[8 * c + 0], s0[8 * c + 1]), pk2(s0[8 * c + 2], s0[8 * c + 3]), pk2(s0[8 * c + 4], s0[8 * c + 5]), pk2(s0[8 * c + 6], s0[8 * c + 7])};
;         else pw = (u32x4){pk2(s1[8 * (c - 2) + 0], s1[8 * (c - 2) + 1]), pk2(s1[8 * (c - 2) + 2], s1[8 * (c - 2) + 3]), pk2(s1[8 * (c - 2) + 4], s1[8 * (c - 2) + 5]), pk2(s1[8 * (c - 2) + 6], s1[8 * (c - 2) + 7])};
;         const bf16x8 pf = __builtin_bit_cast(bf16x8, pw);
;         st.o[0] = mfma32(*(const bf16x8*)(vr + c * 16), pf, st.o[0]);
;         st.o[1] = mfma32(*(const bf16x8*)(vr + 32 * 72 + c * 16), pf, st.o[1]);
;       }
.LBB0_771:
	v_exp_f32_e32 v179, v80
	v_exp_f32_e32 v177, v64
	v_exp_f32_e32 v180, v81
	v_exp_f32_e32 v178, v65
	v_exp_f32_e32 v181, v82
	v_exp_f32_e32 v82, v66
	v_exp_f32_e32 v182, v83
	v_exp_f32_e32 v83, v67
	v_exp_f32_e32 v66, v84
	v_exp_f32_e32 v10, v68
	v_exp_f32_e32 v67, v85
	v_exp_f32_e32 v11, v69
	v_exp_f32_e32 v80, v86
	v_exp_f32_e32 v12, v70
	v_exp_f32_e32 v81, v87
	v_exp_f32_e32 v13, v71
	v_exp_f32_e32 v14, v88
	v_exp_f32_e32 v2, v72
	v_exp_f32_e32 v15, v89
	v_exp_f32_e32 v3, v73
	v_exp_f32_e32 v64, v90
	v_exp_f32_e32 v4, v74
	v_exp_f32_e32 v65, v91
	v_exp_f32_e32 v5, v75
	v_exp_f32_e32 v68, v92
	v_exp_f32_e32 v6, v76
	v_exp_f32_e32 v69, v93
	v_exp_f32_e32 v7, v77
	v_exp_f32_e32 v70, v94
	v_exp_f32_e32 v8, v78
	v_exp_f32_e32 v71, v95
	v_exp_f32_e32 v9, v79
	v_add_f32_e32 v72, v179, v177
	v_add_f32_e32 v72, 0, v72
	v_add_f32_e32 v73, v180, v178
	v_add_f32_e32 v72, v73, v72
	v_add_f32_e32 v73, v181, v82
	v_add_f32_e32 v72, v73, v72
	v_add_f32_e32 v73, v182, v83
	v_add_f32_e32 v74, v73, v72
	v_pk_add_f32 v[72:73], v[66:67], v[10:11]
	v_cvt_pk_bf16_f32 v75, v80, v81
	v_add_f32_e32 v72, v72, v74
	v_add_f32_e32 v74, v73, v72
	v_pk_add_f32 v[72:73], v[80:81], v[12:13]
	v_add_f32_e32 v72, v72, v74
	v_add_f32_e32 v74, v73, v72
	v_pk_add_f32 v[72:73], v[14:15], v[2:3]
	v_add_f32_e32 v72, v72, v74
	v_add_f32_e32 v74, v73, v72
	v_pk_add_f32 v[72:73], v[64:65], v[4:5]
	v_add_f32_e32 v72, v72, v74
	v_add_f32_e32 v74, v73, v72
	v_pk_add_f32 v[72:73], v[68:69], v[6:7]
	v_add_f32_e32 v72, v72, v74
	v_add_f32_e32 v74, v73, v72
	v_pk_add_f32 v[72:73], v[70:71], v[8:9]
	v_add_f32_e32 v72, v72, v74
	v_add_f32_e32 v72, v73, v72
	v_add_f32_e32 v171, v171, v72
	v_lshlrev_b32_e32 v72, 1, v169
	v_add3_u32 v88, v176, v173, v72
	ds_read_b128 v[242:245], v88 offset:13312
	ds_read_b128 v[246:249], v88 offset:13344
	ds_read_b128 v[250:253], v88 offset:17920
	v_cvt_pk_bf16_f32 v72, v179, v180
	v_cvt_pk_bf16_f32 v73, v181, v182
	v_cvt_pk_bf16_f32 v74, v66, v67
	s_waitcnt lgkmcnt(2)
	s_nop 0
	v_mfma_f32_32x32x16_bf16 v[32:47], v[242:245], v[72:75], v[32:47]
	s_waitcnt lgkmcnt(0)
	v_mfma_f32_32x32x16_bf16 v[16:31], v[250:253], v[72:75], v[16:31]
	v_cvt_pk_bf16_f32 v68, v68, v69
	v_cvt_pk_bf16_f32 v69, v70, v71
	v_cvt_pk_bf16_f32 v66, v14, v15
	v_cvt_pk_bf16_f32 v67, v64, v65
	s_nop 1
	v_mfma_f32_32x32x16_bf16 v[32:47], v[246:249], v[66:69], v[32:47]
	v_cvt_pk_bf16_f32 v2, v2, v3
	v_cvt_pk_bf16_f32 v3, v4, v5
	v_cvt_pk_bf16_f32 v4, v6, v7
	v_cvt_pk_bf16_f32 v5, v8, v9
	ds_read_b128 v[6:9], v88 offset:13408
	ds_read_b128 v[70:73], v88 offset:17952
	s_waitcnt lgkmcnt(0)
	v_mfma_f32_32x32x16_bf16 v[16:31], v[70:73], v[66:69], v[16:31]
	v_cvt_pk_bf16_f32 v64, v177, v178
	v_cvt_pk_bf16_f32 v65, v82, v83
	v_cvt_pk_bf16_f32 v66, v10, v11
	v_cvt_pk_bf16_f32 v67, v12, v13
	ds_read_b128 v[10:13], v88 offset:13376
	s_waitcnt lgkmcnt(0)
	v_mfma_f32_32x32x16_bf16 v[32:47], v[10:13], v[64:67], v[32:47]
	ds_read_b128 v[10:13], v88 offset:17984
	v_mfma_f32_32x32x16_bf16 v[32:47], v[6:9], v[2:5], v[32:47]
	ds_read_b128 v[6:9], v88 offset:18016
	s_waitcnt lgkmcnt(1)
	v_mfma_f32_32x32x16_bf16 v[16:31], v[10:13], v[64:67], v[16:31]
	s_waitcnt lgkmcnt(0)
	v_mfma_f32_32x32x16_bf16 v[16:31], v[6:9], v[2:5], v[16:31]
	s_nop 0
	s_branch .LBB0_773

; DI unsigned pk2(float lo, float hi) { f32x2 v = {lo, hi}; return __builtin_bit_cast(unsigned, __builtin_convertvector(v, bfx2)); }
; DI float ex2(float x) { return __builtin_amdgcn_exp2f(x); }
; DI f32x16 mfma32(bf16x8 a, bf16x8 b, f32x16 c) { return __builtin_amdgcn_mfma_f32_32x32x16_bf16(a, b, c, 0, 0, 0); }
; template <int MODE>
; DI void flash_pass(AState& st, const bf16x8* qf, u64 tmask, u64 wmask,
;                    const bf16_t* kbase, size_t kld, const bf16_t* kpe, const bf16_t* vtbase, const float* fbias,
;                    int tq, u64 mysel, bf16_t* smem) {
;     ...
;       for (int r = 0; r < 16; ++r) { e0[r] = ex2(s0[r]); e1[r] = ex2(s1[r]); }
;       if (__any(im > TBITS)) {
;         const float d = im > TBITS ? __int_as_float(im) : 0.f;
;         const float a = ex2(-d);
; #pragma unroll
;         for (int r = 0; r < 16; ++r) { e0[r] = ex2(s0[r] - d); e1[r] = ex2(s1[r] - d); st.o[0][r] *= a; st.o[1][r] *= a; }
;         st.l *= a; st.m += d;
; #pragma unroll
;         for (int r = 0; r < 16; ++r) st.mr[r] = -st.m;
;       }
;       float sum = 0.f;
; #pragma unroll
;       for (int r = 0; r < 16; ++r) { s0[r] = e0[r]; s1[r] = e1[r]; sum += e0[r] + e1[r]; }
;       st.l += sum;
;       const bf16_t* vr = Vs + l31 * 72 + half * 8;
; #pragma unroll
;       for (int c = 0; c < 4; ++c) {
;         u32x4 pw;
;         if (c < 2) pw = (u32x4){pk2(s0[8 * c + 0], s0[8 * c + 1]), pk2(s0[8 * c + 2], s0[8 * c + 3]), pk2(s0[8 * c + 4], s0[8 * c + 5]), pk2(s0[8 * c + 6], s0[8 * c + 7])};
;         else pw = (u32x4){pk2(s1[8 * (c - 2) + 0], s1[8 * (c - 2) + 1]), pk2(s1[8 * (c - 2) + 2], s1[8 * (c - 2) + 3]), pk2(s1[8 * (c - 2) + 4], s1[8 * (c - 2) + 5]), pk2(s1[8 * (c - 2) + 6], s1[8 * (c - 2) + 7])};
;         const bf16x8 pf = __builtin_bit_cast(bf16x8, pw);
;         st.o[0] = mfma32(*(const bf16x8*)(vr + c * 16), pf, st.o[0]);
;         st.o[1] = mfma32(*(const bf16x8*)(vr + 32 * 72 + c * 16), pf, st.o[1]);
;       }
.LBB0_1648:
	ds_read_b128 v[242:245], v0 offset:9216
	ds_read_b128 v[246:249], v0 offset:9248
	ds_read_b128 v[250:253], v0 offset:13856
	v_exp_f32_e32 v152, v80
	v_exp_f32_e32 v150, v81
	v_exp_f32_e32 v149, v82
	v_exp_f32_e32 v82, v66
	v_exp_f32_e32 v151, v83
	v_exp_f32_e32 v83, v67
	v_exp_f32_e32 v80, v84
	v_exp_f32_e32 v81, v85
	v_exp_f32_e32 v2, v86
	v_exp_f32_e32 v6, v70
	v_exp_f32_e32 v3, v87
	v_exp_f32_e32 v7, v71
	v_exp_f32_e32 v66, v76
	v_exp_f32_e32 v67, v77
	v_exp_f32_e32 v70, v78
	v_exp_f32_e32 v71, v79
	v_cvt_pk_bf16_f32 v76, v152, v150
	v_cvt_pk_bf16_f32 v77, v149, v151
	v_cvt_pk_bf16_f32 v78, v80, v81
	v_cvt_pk_bf16_f32 v79, v2, v3
	s_waitcnt lgkmcnt(2)
	s_nop 0
	v_mfma_f32_32x32x16_bf16 v[32:47], v[242:245], v[76:79], v[32:47]
	v_exp_f32_e32 v4, v72
	v_exp_f32_e32 v5, v73
	v_exp_f32_e32 v12, v74
	v_exp_f32_e32 v13, v75
	ds_read_b128 v[72:75], v0 offset:13824
	s_waitcnt lgkmcnt(0)
	v_mfma_f32_32x32x16_bf16 v[16:31], v[72:75], v[76:79], v[16:31]
	v_exp_f32_e32 v147, v64
	v_exp_f32_e32 v148, v65
	v_exp_f32_e32 v8, v68
	v_exp_f32_e32 v9, v69
	v_exp_f32_e32 v10, v88
	v_exp_f32_e32 v11, v89
	v_exp_f32_e32 v14, v90
	v_exp_f32_e32 v15, v91
	v_exp_f32_e32 v64, v92
	v_exp_f32_e32 v65, v93
	v_exp_f32_e32 v68, v94
	v_exp_f32_e32 v69, v95
	v_add_f32_e32 v92, v152, v147
	v_add_f32_e32 v72, 0, v92
	v_add_f32_e32 v73, v150, v148
	v_add_f32_e32 v76, v73, v72
	v_cvt_pk_bf16_f32 v72, v10, v11
	v_cvt_pk_bf16_f32 v73, v14, v15
	v_cvt_pk_bf16_f32 v74, v64, v65
	v_cvt_pk_bf16_f32 v75, v68, v69
	s_nop 1
	v_mfma_f32_32x32x16_bf16 v[32:47], v[246:249], v[72:75], v[32:47]
	v_mfma_f32_32x32x16_bf16 v[16:31], v[250:253], v[72:75], v[16:31]
	v_pk_add_f32 v[80:81], v[80:81], v[8:9]
	v_add_f32_e32 v77, v149, v82
	v_add_f32_e32 v76, v77, v76
	v_add_f32_e32 v77, v151, v83
	v_add_f32_e32 v76, v77, v76
	v_add_f32_e32 v80, v80, v76
	ds_read_b128 v[76:79], v0 offset:9280
	v_cvt_pk_bf16_f32 v73, v82, v83
	v_cvt_pk_bf16_f32 v75, v6, v7
	v_cvt_pk_bf16_f32 v72, v147, v148
	v_cvt_pk_bf16_f32 v74, v8, v9
	s_waitcnt lgkmcnt(0)
	s_nop 0
	v_mfma_f32_32x32x16_bf16 v[32:47], v[76:79], v[72:75], v[32:47]
	v_add_f32_e32 v88, v81, v80
	ds_read_b128 v[80:83], v0 offset:13888
	ds_read_b128 v[84:87], v0 offset:9312
	s_waitcnt lgkmcnt(1)
	v_mfma_f32_32x32x16_bf16 v[16:31], v[80:83], v[72:75], v[16:31]
	v_add_f32_e64 v2, v2, v6
	v_add_f32_e64 v3, v3, v7
	v_add_f32_e32 v2, v2, v88
	v_add_f32_e32 v6, v3, v2
	v_pk_add_f32 v[2:3], v[10:11], v[4:5]
	v_add_f32_e32 v2, v2, v6
	ds_read_b128 v[6:9], v0 offset:13920
	v_add_f32_e32 v10, v3, v2
	v_add_f32_e64 v2, v14, v12
	v_add_f32_e64 v3, v15, v13
	v_add_f32_e32 v0, v2, v10
	v_add_f32_e32 v0, v3, v0
	v_cvt_pk_bf16_f32 v2, v4, v5
	v_cvt_pk_bf16_f32 v3, v12, v13
	v_cvt_pk_bf16_f32 v4, v66, v67
	v_cvt_pk_bf16_f32 v5, v70, v71
	s_waitcnt lgkmcnt(1)
	s_nop 0
	v_mfma_f32_32x32x16_bf16 v[32:47], v[84:87], v[2:5], v[32:47]
	s_waitcnt lgkmcnt(0)
	v_mfma_f32_32x32x16_bf16 v[16:31], v[6:9], v[2:5], v[16:31]
	v_add_f32_e64 v10, v64, v66
	v_add_f32_e64 v11, v65, v67
	v_add_f32_e32 v0, v10, v0
	v_add_f32_e32 v0, v11, v0
	v_pk_add_f32 v[10:11], v[68:69], v[70:71]
	v_add_f32_e32 v0, v10, v0
	v_add_f32_e32 v0, v11, v0
	v_add_f32_e32 v178, v178, v0
	s_branch .LBB0_1650

; DI unsigned pk2(float lo, float hi) { f32x2 v = {lo, hi}; return __builtin_bit_cast(unsigned, __builtin_convertvector(v, bfx2)); }
; DI float ex2(float x) { return __builtin_amdgcn_exp2f(x); }
; DI f32x16 mfma32(bf16x8 a, bf16x8 b, f32x16 c) { return __builtin_amdgcn_mfma_f32_32x32x16_bf16(a, b, c, 0, 0, 0); }
; template <int MODE>
; DI void flash_pass(AState& st, const bf16x8* qf, u64 tmask, u64 wmask,
;                    const bf16_t* kbase, size_t kld, const bf16_t* kpe, const bf16_t* vtbase, const float* fbias,
;                    int tq, u64 mysel, bf16_t* smem) {
;     ...
;       for (int r = 0; r < 16; ++r) { e0[r] = ex2(s0[r]); e1[r] = ex2(s1[r]); }
;       if (__any(im > TBITS)) {
;         const float d = im > TBITS ? __int_as_float(im) : 0.f;
;         const float a = ex2(-d);
; #pragma unroll
;         for (int r = 0; r < 16; ++r) { e0[r] = ex2(s0[r] - d); e1[r] = ex2(s1[r] - d); st.o[0][r] *= a; st.o[1][r] *= a; }
;         st.l *= a; st.m += d;
; #pragma unroll
;         for (int r = 0; r < 16; ++r) st.mr[r] = -st.m;
;       }
;       float sum = 0.f;
; #pragma unroll
;       for (int r = 0; r < 16; ++r) { s0[r] = e0[r]; s1[r] = e1[r]; sum += e0[r] + e1[r]; }
;       st.l += sum;
;       const bf16_t* vr = Vs + l31 * 72 + half * 8;
; #pragma unroll
;       for (int c = 0; c < 4; ++c) {
;         u32x4 pw;
;         if (c < 2) pw = (u32x4){pk2(s0[8 * c + 0], s0[8 * c + 1]), pk2(s0[8 * c + 2], s0[8 * c + 3]), pk2(s0[8 * c + 4], s0[8 * c + 5]), pk2(s0[8 * c + 6], s0[8 * c + 7])};
;         else pw = (u32x4){pk2(s1[8 * (c - 2) + 0], s1[8 * (c - 2) + 1]), pk2(s1[8 * (c - 2) + 2], s1[8 * (c - 2) + 3]), pk2(s1[8 * (c - 2) + 4], s1[8 * (c - 2) + 5]), pk2(s1[8 * (c - 2) + 6], s1[8 * (c - 2) + 7])};
;         const bf16x8 pf = __builtin_bit_cast(bf16x8, pw);
;         st.o[0] = mfma32(*(const bf16x8*)(vr + c * 16), pf, st.o[0]);
;         st.o[1] = mfma32(*(const bf16x8*)(vr + 32 * 72 + c * 16), pf, st.o[1]);
;       }
.LBB0_1677:
	ds_read_b128 v[242:245], v0 offset:9216
	ds_read_b128 v[246:249], v0 offset:9248
	ds_read_b128 v[250:253], v0 offset:13856
	v_exp_f32_e32 v192, v96
	v_exp_f32_e32 v190, v97
	v_exp_f32_e32 v189, v98
	v_exp_f32_e32 v191, v99
	v_exp_f32_e32 v100, v100
	v_exp_f32_e32 v8, v116
	v_exp_f32_e32 v101, v101
	v_exp_f32_e32 v9, v117
	v_exp_f32_e32 v2, v102
	v_exp_f32_e32 v6, v118
	v_exp_f32_e32 v3, v103
	v_exp_f32_e32 v7, v119
	v_cvt_pk_bf16_f32 v116, v192, v190
	v_cvt_pk_bf16_f32 v117, v189, v191
	v_cvt_pk_bf16_f32 v118, v100, v101
	v_cvt_pk_bf16_f32 v119, v2, v3
	s_waitcnt lgkmcnt(2)
	s_nop 0
	v_mfma_f32_32x32x16_bf16 v[64:79], v[242:245], v[116:119], v[64:79]
	v_exp_f32_e32 v14, v106
	v_exp_f32_e32 v15, v107
	v_exp_f32_e32 v96, v108
	v_exp_f32_e32 v97, v109
	ds_read_b128 v[106:109], v0 offset:13824
	s_waitcnt lgkmcnt(0)
	v_mfma_f32_32x32x16_bf16 v[48:63], v[106:109], v[116:119], v[48:63]
	ds_read_b128 v[116:119], v0 offset:9280
	v_exp_f32_e32 v112, v112
	v_exp_f32_e32 v113, v113
	v_exp_f32_e32 v10, v104
	v_exp_f32_e32 v11, v105
	v_exp_f32_e32 v102, v110
	v_exp_f32_e32 v103, v111
	v_add_f32_e32 v110, v192, v112
	v_add_f32_e32 v106, 0, v110
	v_add_f32_e32 v107, v190, v113
	v_add_f32_e32 v110, v107, v106
	v_cvt_pk_bf16_f32 v106, v10, v11
	v_cvt_pk_bf16_f32 v107, v14, v15
	v_cvt_pk_bf16_f32 v108, v96, v97
	v_cvt_pk_bf16_f32 v109, v102, v103
	s_nop 1
	v_mfma_f32_32x32x16_bf16 v[64:79], v[246:249], v[106:109], v[64:79]
	v_mfma_f32_32x32x16_bf16 v[48:63], v[250:253], v[106:109], v[48:63]
	v_exp_f32_e32 v114, v114
	v_exp_f32_e32 v115, v115
	v_cvt_pk_bf16_f32 v106, v112, v113
	v_cvt_pk_bf16_f32 v109, v6, v7
	v_cvt_pk_bf16_f32 v107, v114, v115
	v_cvt_pk_bf16_f32 v108, v8, v9
	s_waitcnt lgkmcnt(0)
	s_nop 0
	v_mfma_f32_32x32x16_bf16 v[64:79], v[116:119], v[106:109], v[64:79]
	v_add_f32_e32 v111, v189, v114
	v_add_f32_e64 v100, v100, v8
	v_add_f32_e32 v110, v111, v110
	v_add_f32_e32 v111, v191, v115
	v_add_f32_e32 v110, v111, v110
	v_add_f32_e32 v100, v100, v110
	ds_read_b128 v[110:113], v0 offset:13888
	s_waitcnt lgkmcnt(0)
	v_mfma_f32_32x32x16_bf16 v[48:63], v[110:113], v[106:109], v[48:63]
	v_exp_f32_e32 v4, v120
	v_exp_f32_e32 v5, v121
	v_exp_f32_e32 v12, v122
	v_exp_f32_e32 v13, v123
	ds_read_b128 v[120:123], v0 offset:9312
	v_exp_f32_e32 v98, v124
	v_exp_f32_e32 v99, v125
	v_exp_f32_e32 v104, v126
	v_exp_f32_e32 v105, v127
	v_add_f32_e64 v101, v101, v9
	v_add_f32_e64 v2, v2, v6
	v_add_f32_e64 v3, v3, v7
	v_add_f32_e32 v100, v101, v100
	v_add_f32_e32 v2, v2, v100
	v_add_f32_e32 v6, v3, v2
	v_pk_add_f32 v[2:3], v[10:11], v[4:5]
	v_add_f32_e32 v2, v2, v6
	ds_read_b128 v[6:9], v0 offset:13920
	v_add_f32_e32 v10, v3, v2
	v_add_f32_e64 v2, v14, v12
	v_add_f32_e64 v3, v15, v13
	v_add_f32_e32 v0, v2, v10
	v_add_f32_e32 v0, v3, v0
	v_cvt_pk_bf16_f32 v2, v4, v5
	v_cvt_pk_bf16_f32 v3, v12, v13
	v_cvt_pk_bf16_f32 v4, v98, v99
	v_cvt_pk_bf16_f32 v5, v104, v105
	s_waitcnt lgkmcnt(1)
	s_nop 0
	v_mfma_f32_32x32x16_bf16 v[64:79], v[120:123], v[2:5], v[64:79]
	s_waitcnt lgkmcnt(0)
	v_mfma_f32_32x32x16_bf16 v[48:63], v[6:9], v[2:5], v[48:63]
	v_add_f32_e64 v10, v96, v98
	v_add_f32_e64 v11, v97, v99
	v_add_f32_e32 v0, v10, v0
	v_add_f32_e32 v0, v11, v0
	v_pk_add_f32 v[10:11], v[102:103], v[104:105]
	v_add_f32_e32 v0, v10, v0
	v_add_f32_e32 v0, v11, v0
	v_add_f32_e32 v169, v169, v0
	s_branch .LBB0_1679

; DI unsigned pk2(float lo, float hi) { f32x2 v = {lo, hi}; return __builtin_bit_cast(unsigned, __builtin_convertvector(v, bfx2)); }
; DI float ex2(float x) { return __builtin_amdgcn_exp2f(x); }
; DI f32x16 mfma32(bf16x8 a, bf16x8 b, f32x16 c) { return __builtin_amdgcn_mfma_f32_32x32x16_bf16(a, b, c, 0, 0, 0); }
; template <int MODE>
; DI void flash_pass(AState& st, const bf16x8* qf, u64 tmask, u64 wmask,
;                    const bf16_t* kbase, size_t kld, const bf16_t* kpe, const bf16_t* vtbase, const float* fbias,
;                    int tq, u64 mysel, bf16_t* smem) {
;     ...
;       for (int r = 0; r < 16; ++r) { e0[r] = ex2(s0[r]); e1[r] = ex2(s1[r]); }
;       if (__any(im > TBITS)) {
;         const float d = im > TBITS ? __int_as_float(im) : 0.f;
;         const float a = ex2(-d);
; #pragma unroll
;         for (int r = 0; r < 16; ++r) { e0[r] = ex2(s0[r] - d); e1[r] = ex2(s1[r] - d); st.o[0][r] *= a; st.o[1][r] *= a; }
;         st.l *= a; st.m += d;
; #pragma unroll
;         for (int r = 0; r < 16; ++r) st.mr[r] = -st.m;
;       }
;       float sum = 0.f;
; #pragma unroll
;       for (int r = 0; r < 16; ++r) { s0[r] = e0[r]; s1[r] = e1[r]; sum += e0[r] + e1[r]; }
;       st.l += sum;
;       const bf16_t* vr = Vs + l31 * 72 + half * 8;
; #pragma unroll
;       for (int c = 0; c < 4; ++c) {
;         u32x4 pw;
;         if (c < 2) pw = (u32x4){pk2(s0[8 * c + 0], s0[8 * c + 1]), pk2(s0[8 * c + 2], s0[8 * c + 3]), pk2(s0[8 * c + 4], s0[8 * c + 5]), pk2(s0[8 * c + 6], s0[8 * c + 7])};
;         else pw = (u32x4){pk2(s1[8 * (c - 2) + 0], s1[8 * (c - 2) + 1]), pk2(s1[8 * (c - 2) + 2], s1[8 * (c - 2) + 3]), pk2(s1[8 * (c - 2) + 4], s1[8 * (c - 2) + 5]), pk2(s1[8 * (c - 2) + 6], s1[8 * (c - 2) + 7])};
;         const bf16x8 pf = __builtin_bit_cast(bf16x8, pw);
;         st.o[0] = mfma32(*(const bf16x8*)(vr + c * 16), pf, st.o[0]);
;         st.o[1] = mfma32(*(const bf16x8*)(vr + 32 * 72 + c * 16), pf, st.o[1]);
;       }
.LBB0_1725:
	ds_read_b128 v[242:245], v0 offset:9216
	ds_read_b128 v[106:109], v0 offset:9248
	ds_read_b128 v[246:249], v0 offset:13856
	ds_read_b128 v[250:253], v0 offset:13824
	v_exp_f32_e32 v101, v156
	v_exp_f32_e32 v99, v157
	v_exp_f32_e32 v98, v158
	v_exp_f32_e32 v100, v159
	v_exp_f32_e32 v92, v14
	v_exp_f32_e32 v90, v10
	v_exp_f32_e32 v93, v15
	v_exp_f32_e32 v91, v11
	v_exp_f32_e32 v10, v84
	v_exp_f32_e32 v11, v85
	v_cvt_pk_bf16_f32 v102, v101, v99
	v_cvt_pk_bf16_f32 v103, v98, v100
	v_cvt_pk_bf16_f32 v104, v92, v93
	v_cvt_pk_bf16_f32 v105, v10, v11
	s_waitcnt lgkmcnt(3)
	s_nop 0
	v_mfma_f32_32x32x16_bf16 v[32:47], v[242:245], v[102:105], v[32:47]
	s_waitcnt lgkmcnt(0)
	v_mfma_f32_32x32x16_bf16 v[16:31], v[250:253], v[102:105], v[16:31]
	v_exp_f32_e32 v94, v160
	v_exp_f32_e32 v95, v161
	v_exp_f32_e32 v84, v88
	v_exp_f32_e32 v14, v86
	v_exp_f32_e32 v85, v89
	v_exp_f32_e32 v15, v87
	v_exp_f32_e32 v82, v82
	v_exp_f32_e32 v83, v83
	v_exp_f32_e32 v8, v8
	v_exp_f32_e32 v9, v9
	v_exp_f32_e32 v2, v2
	v_exp_f32_e32 v3, v3
	v_add_f32_e32 v101, v101, v94
	v_add_f32_e32 v86, 0, v101
	v_add_f32_e32 v87, v99, v95
	v_add_f32_e32 v99, v87, v86
	v_cvt_pk_bf16_f32 v86, v84, v85
	v_cvt_pk_bf16_f32 v87, v82, v83
	v_cvt_pk_bf16_f32 v88, v8, v9
	v_cvt_pk_bf16_f32 v89, v2, v3
	s_nop 1
	v_mfma_f32_32x32x16_bf16 v[32:47], v[106:109], v[86:89], v[32:47]
	v_mfma_f32_32x32x16_bf16 v[16:31], v[246:249], v[86:89], v[16:31]
	v_exp_f32_e32 v96, v96
	v_exp_f32_e32 v97, v97
	v_exp_f32_e32 v80, v80
	v_exp_f32_e32 v81, v81
	v_add_f32_e32 v98, v98, v96
	v_add_f32_e64 v92, v92, v90
	v_add_f32_e32 v98, v98, v99
	v_add_f32_e32 v99, v100, v97
	v_add_f32_e32 v98, v99, v98
	v_add_f32_e32 v92, v92, v98
	ds_read_b128 v[98:101], v0 offset:9280
	v_cvt_pk_bf16_f32 v86, v94, v95
	v_cvt_pk_bf16_f32 v87, v96, v97
	v_cvt_pk_bf16_f32 v88, v90, v91
	v_cvt_pk_bf16_f32 v89, v80, v81
	s_waitcnt lgkmcnt(0)
	s_nop 0
	v_mfma_f32_32x32x16_bf16 v[32:47], v[98:101], v[86:89], v[32:47]
	v_add_f32_e64 v93, v93, v91
	v_add_f32_e32 v102, v93, v92
	ds_read_b128 v[90:93], v0 offset:13888
	ds_read_b128 v[94:97], v0 offset:9312
	ds_read_b128 v[98:101], v0 offset:13920
	s_waitcnt lgkmcnt(2)
	v_mfma_f32_32x32x16_bf16 v[16:31], v[90:93], v[86:89], v[16:31]
	v_exp_f32_e32 v12, v12
	v_exp_f32_e32 v13, v13
	v_exp_f32_e32 v6, v6
	v_exp_f32_e32 v7, v7
	v_exp_f32_e32 v4, v4
	v_exp_f32_e32 v5, v5
	v_add_f32_e64 v10, v10, v80
	v_add_f32_e64 v11, v11, v81
	v_add_f32_e32 v10, v10, v102
	v_add_f32_e32 v80, v11, v10
	v_pk_add_f32 v[10:11], v[84:85], v[14:15]
	v_add_f32_e32 v10, v10, v80
	v_add_f32_e32 v80, v11, v10
	v_add_f32_e64 v10, v82, v12
	v_add_f32_e64 v11, v83, v13
	v_add_f32_e32 v0, v10, v80
	v_add_f32_e32 v0, v11, v0
	v_cvt_pk_bf16_f32 v10, v14, v15
	v_cvt_pk_bf16_f32 v11, v12, v13
	v_cvt_pk_bf16_f32 v12, v6, v7
	v_cvt_pk_bf16_f32 v13, v4, v5
	s_waitcnt lgkmcnt(1)
	s_nop 0
	v_mfma_f32_32x32x16_bf16 v[32:47], v[94:97], v[10:13], v[32:47]
	s_waitcnt lgkmcnt(0)
	v_mfma_f32_32x32x16_bf16 v[16:31], v[98:101], v[10:13], v[16:31]
	v_add_f32_e64 v2, v2, v4
	v_add_f32_e64 v3, v3, v5
	v_add_f32_e64 v6, v8, v6
	v_add_f32_e64 v7, v9, v7
	v_add_f32_e32 v0, v6, v0
	v_add_f32_e32 v0, v7, v0
	v_add_f32_e32 v0, v2, v0
	v_add_f32_e32 v0, v3, v0
	v_add_f32_e32 v173, v173, v0
	s_branch .LBB0_1727

; DI unsigned pk2(float lo, float hi) { f32x2 v = {lo, hi}; return __builtin_bit_cast(unsigned, __builtin_convertvector(v, bfx2)); }
; DI float ex2(float x) { return __builtin_amdgcn_exp2f(x); }
; DI f32x16 mfma32(bf16x8 a, bf16x8 b, f32x16 c) { return __builtin_amdgcn_mfma_f32_32x32x16_bf16(a, b, c, 0, 0, 0); }
; template <int MODE>
; DI void flash_pass(AState& st, const bf16x8* qf, u64 tmask, u64 wmask,
;                    const bf16_t* kbase, size_t kld, const bf16_t* kpe, const bf16_t* vtbase, const float* fbias,
;                    int tq, u64 mysel, bf16_t* smem) {
;     ...
;       for (int r = 0; r < 16; ++r) { e0[r] = ex2(s0[r]); e1[r] = ex2(s1[r]); }
;       if (__any(im > TBITS)) {
;         const float d = im > TBITS ? __int_as_float(im) : 0.f;
;         const float a = ex2(-d);
; #pragma unroll
;         for (int r = 0; r < 16; ++r) { e0[r] = ex2(s0[r] - d); e1[r] = ex2(s1[r] - d); st.o[0][r] *= a; st.o[1][r] *= a; }
;         st.l *= a; st.m += d;
; #pragma unroll
;         for (int r = 0; r < 16; ++r) st.mr[r] = -st.m;
;       }
;       float sum = 0.f;
; #pragma unroll
;       for (int r = 0; r < 16; ++r) { s0[r] = e0[r]; s1[r] = e1[r]; sum += e0[r] + e1[r]; }
;       st.l += sum;
;       const bf16_t* vr = Vs + l31 * 72 + half * 8;
; #pragma unroll
;       for (int c = 0; c < 4; ++c) {
;         u32x4 pw;
;         if (c < 2) pw = (u32x4){pk2(s0[8 * c + 0], s0[8 * c + 1]), pk2(s0[8 * c + 2], s0[8 * c + 3]), pk2(s0[8 * c + 4], s0[8 * c + 5]), pk2(s0[8 * c + 6], s0[8 * c + 7])};
;         else pw = (u32x4){pk2(s1[8 * (c - 2) + 0], s1[8 * (c - 2) + 1]), pk2(s1[8 * (c - 2) + 2], s1[8 * (c - 2) + 3]), pk2(s1[8 * (c - 2) + 4], s1[8 * (c - 2) + 5]), pk2(s1[8 * (c - 2) + 6], s1[8 * (c - 2) + 7])};
;         const bf16x8 pf = __builtin_bit_cast(bf16x8, pw);
;         st.o[0] = mfma32(*(const bf16x8*)(vr + c * 16), pf, st.o[0]);
;         st.o[1] = mfma32(*(const bf16x8*)(vr + 32 * 72 + c * 16), pf, st.o[1]);
;       }
.LBB0_1793:
	v_exp_f32_e32 v181, v64
	v_exp_f32_e32 v179, v65
	v_exp_f32_e32 v178, v66
	v_exp_f32_e32 v180, v67
	v_exp_f32_e32 v68, v68
	v_exp_f32_e32 v8, v84
	v_exp_f32_e32 v69, v69
	v_exp_f32_e32 v9, v85
	v_exp_f32_e32 v2, v70
	v_exp_f32_e32 v6, v86
	v_exp_f32_e32 v3, v71
	v_exp_f32_e32 v7, v87
	v_exp_f32_e32 v14, v74
	v_lshlrev_b32_e32 v74, 1, v169
	v_add3_u32 v177, v177, v173, v74
	ds_read_b128 v[242:245], v177 offset:13312
	ds_read_b128 v[246:249], v177 offset:13344
	ds_read_b128 v[250:253], v177 offset:17952
	v_cvt_pk_bf16_f32 v84, v181, v179
	v_cvt_pk_bf16_f32 v85, v178, v180
	v_cvt_pk_bf16_f32 v86, v68, v69
	v_cvt_pk_bf16_f32 v87, v2, v3
	s_waitcnt lgkmcnt(2)
	s_nop 0
	v_mfma_f32_32x32x16_bf16 v[32:47], v[242:245], v[84:87], v[32:47]
	v_exp_f32_e32 v15, v75
	v_exp_f32_e32 v64, v76
	v_exp_f32_e32 v65, v77
	ds_read_b128 v[74:77], v177 offset:17920
	s_waitcnt lgkmcnt(0)
	v_mfma_f32_32x32x16_bf16 v[16:31], v[74:77], v[84:87], v[16:31]
	ds_read_b128 v[84:87], v177 offset:13376
	v_exp_f32_e32 v80, v80
	v_exp_f32_e32 v81, v81
	v_exp_f32_e32 v10, v72
	v_exp_f32_e32 v11, v73
	v_exp_f32_e32 v70, v78
	v_exp_f32_e32 v71, v79
	v_add_f32_e32 v78, v181, v80
	v_add_f32_e32 v74, 0, v78
	v_add_f32_e32 v75, v179, v81
	v_add_f32_e32 v78, v75, v74
	v_cvt_pk_bf16_f32 v74, v10, v11
	v_cvt_pk_bf16_f32 v75, v14, v15
	v_cvt_pk_bf16_f32 v76, v64, v65
	v_cvt_pk_bf16_f32 v77, v70, v71
	s_nop 1
	v_mfma_f32_32x32x16_bf16 v[32:47], v[246:249], v[74:77], v[32:47]
	v_mfma_f32_32x32x16_bf16 v[16:31], v[250:253], v[74:77], v[16:31]
	v_exp_f32_e32 v82, v82
	v_exp_f32_e32 v83, v83
	v_cvt_pk_bf16_f32 v74, v80, v81
	v_cvt_pk_bf16_f32 v77, v6, v7
	v_cvt_pk_bf16_f32 v75, v82, v83
	v_cvt_pk_bf16_f32 v76, v8, v9
	s_waitcnt lgkmcnt(0)
	s_nop 0
	v_mfma_f32_32x32x16_bf16 v[32:47], v[84:87], v[74:77], v[32:47]
	v_add_f32_e32 v79, v178, v82
	v_add_f32_e64 v68, v68, v8
	v_add_f32_e32 v78, v79, v78
	v_add_f32_e32 v79, v180, v83
	v_add_f32_e32 v78, v79, v78
	v_add_f32_e32 v68, v68, v78
	ds_read_b128 v[78:81], v177 offset:17984
	s_waitcnt lgkmcnt(0)
	v_mfma_f32_32x32x16_bf16 v[16:31], v[78:81], v[74:77], v[16:31]
	v_exp_f32_e32 v4, v88
	v_exp_f32_e32 v5, v89
	v_exp_f32_e32 v12, v90
	v_exp_f32_e32 v13, v91
	ds_read_b128 v[88:91], v177 offset:13408
	v_exp_f32_e32 v66, v92
	v_exp_f32_e32 v67, v93
	v_exp_f32_e32 v72, v94
	v_exp_f32_e32 v73, v95
	v_add_f32_e64 v69, v69, v9
	v_add_f32_e64 v2, v2, v6
	v_add_f32_e64 v3, v3, v7
	v_add_f32_e32 v68, v69, v68
	v_add_f32_e32 v2, v2, v68
	v_add_f32_e32 v6, v3, v2
	v_pk_add_f32 v[2:3], v[10:11], v[4:5]
	v_add_f32_e32 v2, v2, v6
	ds_read_b128 v[6:9], v177 offset:18016
	v_add_f32_e32 v10, v3, v2
	v_add_f32_e64 v2, v14, v12
	v_add_f32_e64 v3, v15, v13
	v_add_f32_e32 v2, v2, v10
	v_add_f32_e32 v14, v3, v2
	v_cvt_pk_bf16_f32 v2, v4, v5
	v_cvt_pk_bf16_f32 v3, v12, v13
	v_cvt_pk_bf16_f32 v4, v66, v67
	v_cvt_pk_bf16_f32 v5, v72, v73
	s_waitcnt lgkmcnt(1)
	s_nop 0
	v_mfma_f32_32x32x16_bf16 v[32:47], v[88:91], v[2:5], v[32:47]
	s_waitcnt lgkmcnt(0)
	v_mfma_f32_32x32x16_bf16 v[16:31], v[6:9], v[2:5], v[16:31]
	v_add_f32_e64 v10, v64, v66
	v_add_f32_e64 v11, v65, v67
	v_add_f32_e32 v10, v10, v14
	v_add_f32_e32 v12, v11, v10
	v_pk_add_f32 v[10:11], v[70:71], v[72:73]
	v_add_f32_e32 v10, v10, v12
	v_add_f32_e32 v10, v11, v10
	v_add_f32_e32 v171, v171, v10
	s_branch .LBB0_1795

; DI unsigned pk2(float lo, float hi) { f32x2 v = {lo, hi}; return __builtin_bit_cast(unsigned, __builtin_convertvector(v, bfx2)); }
; DI float ex2(float x) { return __builtin_amdgcn_exp2f(x); }
; DI f32x16 mfma32(bf16x8 a, bf16x8 b, f32x16 c) { return __builtin_amdgcn_mfma_f32_32x32x16_bf16(a, b, c, 0, 0, 0); }
; template <int MODE>
; DI void flash_pass(AState& st, const bf16x8* qf, u64 tmask, u64 wmask,
;                    const bf16_t* kbase, size_t kld, const bf16_t* kpe, const bf16_t* vtbase, const float* fbias,
;                    int tq, u64 mysel, bf16_t* smem) {
;     ...
;       for (int r = 0; r < 16; ++r) { e0[r] = ex2(s0[r]); e1[r] = ex2(s1[r]); }
;       if (__any(im > TBITS)) {
;         const float d = im > TBITS ? __int_as_float(im) : 0.f;
;         const float a = ex2(-d);
; #pragma unroll
;         for (int r = 0; r < 16; ++r) { e0[r] = ex2(s0[r] - d); e1[r] = ex2(s1[r] - d); st.o[0][r] *= a; st.o[1][r] *= a; }
;         st.l *= a; st.m += d;
; #pragma unroll
;         for (int r = 0; r < 16; ++r) st.mr[r] = -st.m;
;       }
;       float sum = 0.f;
; #pragma unroll
;       for (int r = 0; r < 16; ++r) { s0[r] = e0[r]; s1[r] = e1[r]; sum += e0[r] + e1[r]; }
;       st.l += sum;
;       const bf16_t* vr = Vs + l31 * 72 + half * 8;
; #pragma unroll
;       for (int c = 0; c < 4; ++c) {
;         u32x4 pw;
;         if (c < 2) pw = (u32x4){pk2(s0[8 * c + 0], s0[8 * c + 1]), pk2(s0[8 * c + 2], s0[8 * c + 3]), pk2(s0[8 * c + 4], s0[8 * c + 5]), pk2(s0[8 * c + 6], s0[8 * c + 7])};
;         else pw = (u32x4){pk2(s1[8 * (c - 2) + 0], s1[8 * (c - 2) + 1]), pk2(s1[8 * (c - 2) + 2], s1[8 * (c - 2) + 3]), pk2(s1[8 * (c - 2) + 4], s1[8 * (c - 2) + 5]), pk2(s1[8 * (c - 2) + 6], s1[8 * (c - 2) + 7])};
;         const bf16x8 pf = __builtin_bit_cast(bf16x8, pw);
;         st.o[0] = mfma32(*(const bf16x8*)(vr + c * 16), pf, st.o[0]);
;         st.o[1] = mfma32(*(const bf16x8*)(vr + 32 * 72 + c * 16), pf, st.o[1]);
;       }
.LBB0_1805:
	v_exp_f32_e32 v180, v64
	v_exp_f32_e32 v178, v65
	v_exp_f32_e32 v177, v66
	v_exp_f32_e32 v179, v67
	v_exp_f32_e32 v68, v68
	v_exp_f32_e32 v8, v84
	v_exp_f32_e32 v69, v69
	v_exp_f32_e32 v9, v85
	v_exp_f32_e32 v2, v70
	v_exp_f32_e32 v6, v86
	v_exp_f32_e32 v3, v71
	v_exp_f32_e32 v7, v87
	v_exp_f32_e32 v14, v74
	v_lshlrev_b32_e32 v74, 1, v169
	v_add3_u32 v176, v176, v173, v74
	ds_read_b128 v[242:245], v176 offset:13312
	ds_read_b128 v[246:249], v176 offset:13344
	ds_read_b128 v[250:253], v176 offset:17952
	v_cvt_pk_bf16_f32 v84, v180, v178
	v_cvt_pk_bf16_f32 v85, v177, v179
	v_cvt_pk_bf16_f32 v86, v68, v69
	v_cvt_pk_bf16_f32 v87, v2, v3
	s_waitcnt lgkmcnt(2)
	s_nop 0
	v_mfma_f32_32x32x16_bf16 v[32:47], v[242:245], v[84:87], v[32:47]
	v_exp_f32_e32 v15, v75
	v_exp_f32_e32 v64, v76
	v_exp_f32_e32 v65, v77
	ds_read_b128 v[74:77], v176 offset:17920
	s_waitcnt lgkmcnt(0)
	v_mfma_f32_32x32x16_bf16 v[16:31], v[74:77], v[84:87], v[16:31]
	ds_read_b128 v[84:87], v176 offset:13376
	v_exp_f32_e32 v80, v80
	v_exp_f32_e32 v81, v81
	v_exp_f32_e32 v10, v72
	v_exp_f32_e32 v11, v73
	v_exp_f32_e32 v70, v78
	v_exp_f32_e32 v71, v79
	v_add_f32_e32 v78, v180, v80
	v_add_f32_e32 v74, 0, v78
	v_add_f32_e32 v75, v178, v81
	v_add_f32_e32 v78, v75, v74
	v_cvt_pk_bf16_f32 v74, v10, v11
	v_cvt_pk_bf16_f32 v75, v14, v15
	v_cvt_pk_bf16_f32 v76, v64, v65
	v_cvt_pk_bf16_f32 v77, v70, v71
	s_nop 1
	v_mfma_f32_32x32x16_bf16 v[32:47], v[246:249], v[74:77], v[32:47]
	v_mfma_f32_32x32x16_bf16 v[16:31], v[250:253], v[74:77], v[16:31]
	v_exp_f32_e32 v82, v82
	v_exp_f32_e32 v83, v83
	v_cvt_pk_bf16_f32 v74, v80, v81
	v_cvt_pk_bf16_f32 v77, v6, v7
	v_cvt_pk_bf16_f32 v75, v82, v83
	v_cvt_pk_bf16_f32 v76, v8, v9
	s_waitcnt lgkmcnt(0)
	s_nop 0
	v_mfma_f32_32x32x16_bf16 v[32:47], v[84:87], v[74:77], v[32:47]
	v_add_f32_e32 v79, v177, v82
	v_add_f32_e64 v68, v68, v8
	v_add_f32_e32 v78, v79, v78
	v_add_f32_e32 v79, v179, v83
	v_add_f32_e32 v78, v79, v78
	v_add_f32_e32 v68, v68, v78
	ds_read_b128 v[78:81], v176 offset:17984
	s_waitcnt lgkmcnt(0)
	v_mfma_f32_32x32x16_bf16 v[16:31], v[78:81], v[74:77], v[16:31]
	v_exp_f32_e32 v4, v88
	v_exp_f32_e32 v5, v89
	v_exp_f32_e32 v12, v90
	v_exp_f32_e32 v13, v91
	ds_read_b128 v[88:91], v176 offset:13408
	v_exp_f32_e32 v66, v92
	v_exp_f32_e32 v67, v93
	v_exp_f32_e32 v72, v94
	v_exp_f32_e32 v73, v95
	v_add_f32_e64 v69, v69, v9
	v_add_f32_e64 v2, v2, v6
	v_add_f32_e64 v3, v3, v7
	v_add_f32_e32 v68, v69, v68
	v_add_f32_e32 v2, v2, v68
	v_add_f32_e32 v6, v3, v2
	v_pk_add_f32 v[2:3], v[10:11], v[4:5]
	v_add_f32_e32 v2, v2, v6
	ds_read_b128 v[6:9], v176 offset:18016
	v_add_f32_e32 v10, v3, v2
	v_add_f32_e64 v2, v14, v12
	v_add_f32_e64 v3, v15, v13
	v_add_f32_e32 v2, v2, v10
	v_add_f32_e32 v14, v3, v2
	v_cvt_pk_bf16_f32 v2, v4, v5
	v_cvt_pk_bf16_f32 v3, v12, v13
	v_cvt_pk_bf16_f32 v4, v66, v67
	v_cvt_pk_bf16_f32 v5, v72, v73
	s_waitcnt lgkmcnt(1)
	s_nop 0
	v_mfma_f32_32x32x16_bf16 v[32:47], v[88:91], v[2:5], v[32:47]
	s_waitcnt lgkmcnt(0)
	v_mfma_f32_32x32x16_bf16 v[16:31], v[6:9], v[2:5], v[16:31]
	v_add_f32_e64 v10, v64, v66
	v_add_f32_e64 v11, v65, v67
	v_add_f32_e32 v10, v10, v14
	v_add_f32_e32 v12, v11, v10
	v_pk_add_f32 v[10:11], v[70:71], v[72:73]
	v_add_f32_e32 v10, v10, v12
	v_add_f32_e32 v10, v11, v10
	v_add_f32_e32 v171, v171, v10
	s_branch .LBB0_1807
